# P1 side job balance: the 136 three-unit workgroups convert the first 16.6 percent of the cached latent rows after their GEMM units, the 120 two-unit workgroups the rest
# baseline (speedup 1.0000x reference)
.LBB0_577:
	s_cmpk_lg_i32 s59, 0x100
	v_readlane_b32 s62, v245, 37
	v_readlane_b32 s63, v245, 38
	s_cbranch_scc1 .LBB0_593
	s_cmpk_lt_u32 s96, 0x88
	s_cbranch_scc0 .Lcv_regionB
	s_load_dwordx2 s[0:1], s[62:63], 0x28
	s_lshl_b32 s2, s96, 9
	v_add_u32_e32 v2, s2, v0
	v_mov_b32_e32 v3, 0
	s_mov_b64 s[42:43], 0x110000
	s_mov_b64 s[44:45], 0x88000
	v_lshl_add_u64 v[12:13], v[2:3], 3, s[34:35]
	s_waitcnt lgkmcnt(0)
	v_lshl_add_u64 v[10:11], v[2:3], 4, s[0:1]
	s_mov_b64 s[0:1], 0x16d00000
	v_lshl_add_u64 v[12:13], v[12:13], 0, s[0:1]
	global_load_dwordx4 v[64:67], v[10:11], off nt
	v_lshl_add_u64 v[62:63], v[10:11], 0, s[42:43]
	global_load_dwordx4 v[68:71], v[62:63], off nt
	v_lshl_add_u64 v[62:63], v[62:63], 0, s[42:43]
	global_load_dwordx4 v[72:75], v[62:63], off nt
	v_lshl_add_u64 v[62:63], v[62:63], 0, s[42:43]
	global_load_dwordx4 v[76:79], v[62:63], off nt
	v_lshl_add_u64 v[62:63], v[62:63], 0, s[42:43]
	global_load_dwordx4 v[80:83], v[62:63], off nt
	v_lshl_add_u64 v[62:63], v[62:63], 0, s[42:43]
	global_load_dwordx4 v[84:87], v[62:63], off nt
	v_lshl_add_u64 v[62:63], v[62:63], 0, s[42:43]
	global_load_dwordx4 v[88:91], v[62:63], off nt
	v_lshl_add_u64 v[62:63], v[62:63], 0, s[42:43]
	global_load_dwordx4 v[92:95], v[62:63], off nt
	v_lshl_add_u64 v[62:63], v[62:63], 0, s[42:43]
	global_load_dwordx4 v[96:99], v[62:63], off nt
	v_lshl_add_u64 v[62:63], v[62:63], 0, s[42:43]
	global_load_dwordx4 v[100:103], v[62:63], off nt
	v_lshl_add_u64 v[62:63], v[62:63], 0, s[42:43]
	global_load_dwordx4 v[104:107], v[62:63], off nt
	v_lshl_add_u64 v[62:63], v[62:63], 0, s[42:43]
	global_load_dwordx4 v[108:111], v[62:63], off nt
	v_lshl_add_u64 v[62:63], v[62:63], 0, s[42:43]
	global_load_dwordx4 v[112:115], v[62:63], off nt
	v_lshl_add_u64 v[62:63], v[62:63], 0, s[42:43]
	global_load_dwordx4 v[116:119], v[62:63], off nt
	v_lshl_add_u64 v[62:63], v[62:63], 0, s[42:43]
	global_load_dwordx4 v[120:123], v[62:63], off nt
	v_lshl_add_u64 v[62:63], v[62:63], 0, s[42:43]
	global_load_dwordx4 v[124:127], v[62:63], off nt
	v_lshl_add_u64 v[62:63], v[62:63], 0, s[42:43]
	global_load_dwordx4 v[128:131], v[62:63], off nt
	v_lshl_add_u64 v[62:63], v[62:63], 0, s[42:43]
	global_load_dwordx4 v[132:135], v[62:63], off nt
	v_lshl_add_u64 v[62:63], v[62:63], 0, s[42:43]
	global_load_dwordx4 v[140:143], v[62:63], off nt
	v_lshl_add_u64 v[62:63], v[62:63], 0, s[42:43]
	global_load_dwordx4 v[144:147], v[62:63], off nt
	s_waitcnt vmcnt(19)
	v_cvt_pk_bf16_f32 v64, v64, v65
	v_cvt_pk_bf16_f32 v65, v66, v67
	global_store_dwordx2 v[12:13], v[64:65], off
	s_waitcnt vmcnt(19)
	v_cvt_pk_bf16_f32 v68, v68, v69
	v_cvt_pk_bf16_f32 v69, v70, v71
	v_lshl_add_u64 v[62:63], v[12:13], 0, s[44:45]
	global_store_dwordx2 v[62:63], v[68:69], off
	s_waitcnt vmcnt(19)
	v_cvt_pk_bf16_f32 v72, v72, v73
	v_cvt_pk_bf16_f32 v73, v74, v75
	v_lshl_add_u64 v[62:63], v[62:63], 0, s[44:45]
	global_store_dwordx2 v[62:63], v[72:73], off
	s_waitcnt vmcnt(19)
	v_cvt_pk_bf16_f32 v76, v76, v77
	v_cvt_pk_bf16_f32 v77, v78, v79
	v_lshl_add_u64 v[62:63], v[62:63], 0, s[44:45]
	global_store_dwordx2 v[62:63], v[76:77], off
	s_waitcnt vmcnt(19)
	v_cvt_pk_bf16_f32 v80, v80, v81
	v_cvt_pk_bf16_f32 v81, v82, v83
	v_lshl_add_u64 v[62:63], v[62:63], 0, s[44:45]
	global_store_dwordx2 v[62:63], v[80:81], off
	s_waitcnt vmcnt(19)
	v_cvt_pk_bf16_f32 v84, v84, v85
	v_cvt_pk_bf16_f32 v85, v86, v87
	v_lshl_add_u64 v[62:63], v[62:63], 0, s[44:45]
	global_store_dwordx2 v[62:63], v[84:85], off
	s_waitcnt vmcnt(19)
	v_cvt_pk_bf16_f32 v88, v88, v89
	v_cvt_pk_bf16_f32 v89, v90, v91
	v_lshl_add_u64 v[62:63], v[62:63], 0, s[44:45]
	global_store_dwordx2 v[62:63], v[88:89], off
	s_waitcnt vmcnt(19)
	v_cvt_pk_bf16_f32 v92, v92, v93
	v_cvt_pk_bf16_f32 v93, v94, v95
	v_lshl_add_u64 v[62:63], v[62:63], 0, s[44:45]
	global_store_dwordx2 v[62:63], v[92:93], off
	s_waitcnt vmcnt(19)
	v_cvt_pk_bf16_f32 v96, v96, v97
	v_cvt_pk_bf16_f32 v97, v98, v99
	v_lshl_add_u64 v[62:63], v[62:63], 0, s[44:45]
	global_store_dwordx2 v[62:63], v[96:97], off
	s_waitcnt vmcnt(19)
	v_cvt_pk_bf16_f32 v100, v100, v101
	v_cvt_pk_bf16_f32 v101, v102, v103
	v_lshl_add_u64 v[62:63], v[62:63], 0, s[44:45]
	global_store_dwordx2 v[62:63], v[100:101], off
	s_waitcnt vmcnt(19)
	v_cvt_pk_bf16_f32 v104, v104, v105
	v_cvt_pk_bf16_f32 v105, v106, v107
	v_lshl_add_u64 v[62:63], v[62:63], 0, s[44:45]
	global_store_dwordx2 v[62:63], v[104:105], off
	s_waitcnt vmcnt(19)
	v_cvt_pk_bf16_f32 v108, v108, v109
	v_cvt_pk_bf16_f32 v109, v110, v111
	v_lshl_add_u64 v[62:63], v[62:63], 0, s[44:45]
	global_store_dwordx2 v[62:63], v[108:109], off
	s_waitcnt vmcnt(19)
	v_cvt_pk_bf16_f32 v112, v112, v113
	v_cvt_pk_bf16_f32 v113, v114, v115
	v_lshl_add_u64 v[62:63], v[62:63], 0, s[44:45]
	global_store_dwordx2 v[62:63], v[112:113], off
	s_waitcnt vmcnt(19)
	v_cvt_pk_bf16_f32 v116, v116, v117
	v_cvt_pk_bf16_f32 v117, v118, v119
	v_lshl_add_u64 v[62:63], v[62:63], 0, s[44:45]
	global_store_dwordx2 v[62:63], v[116:117], off
	s_waitcnt vmcnt(19)
	v_cvt_pk_bf16_f32 v120, v120, v121
	v_cvt_pk_bf16_f32 v121, v122, v123
	v_lshl_add_u64 v[62:63], v[62:63], 0, s[44:45]
	global_store_dwordx2 v[62:63], v[120:121], off
	s_waitcnt vmcnt(19)
	v_cvt_pk_bf16_f32 v124, v124, v125
	v_cvt_pk_bf16_f32 v125, v126, v127
	v_lshl_add_u64 v[62:63], v[62:63], 0, s[44:45]
	global_store_dwordx2 v[62:63], v[124:125], off
	s_waitcnt vmcnt(19)
	v_cvt_pk_bf16_f32 v128, v128, v129
	v_cvt_pk_bf16_f32 v129, v130, v131
	v_lshl_add_u64 v[62:63], v[62:63], 0, s[44:45]
	global_store_dwordx2 v[62:63], v[128:129], off
	s_waitcnt vmcnt(19)
	v_cvt_pk_bf16_f32 v132, v132, v133
	v_cvt_pk_bf16_f32 v133, v134, v135
	v_lshl_add_u64 v[62:63], v[62:63], 0, s[44:45]
	global_store_dwordx2 v[62:63], v[132:133], off
	s_waitcnt vmcnt(19)
	v_cvt_pk_bf16_f32 v140, v140, v141
	v_cvt_pk_bf16_f32 v141, v142, v143
	v_lshl_add_u64 v[62:63], v[62:63], 0, s[44:45]
	global_store_dwordx2 v[62:63], v[140:141], off
	s_waitcnt vmcnt(19)
	v_cvt_pk_bf16_f32 v144, v144, v145
	v_cvt_pk_bf16_f32 v145, v146, v147
	v_lshl_add_u64 v[62:63], v[62:63], 0, s[44:45]
	global_store_dwordx2 v[62:63], v[144:145], off
	s_branch .LBB0_593
.Lcv_regionB:
	s_add_i32 s6, s96, 0xffffff78
	s_ashr_i32 s7, s6, 31
	s_lshl_b64 s[0:1], s[6:7], 9
	v_or_b32_e32 v2, s0, v0
	v_mov_b32_e32 v3, s1
	s_mov_b64 s[0:1], 0x69000
	v_lshl_add_u64 v[6:7], v[2:3], 0, s[0:1]
	s_mov_b64 s[0:1], 0x6ac000
	v_mov_b32_e32 v13, 0
	v_cmp_gt_u64_e32 vcc, s[0:1], v[6:7]
	v_lshlrev_b32_e32 v4, 3, v0
	v_mov_b64_e32 v[8:9], v[2:3]
	s_and_saveexec_b64 s[8:9], vcc
	s_cbranch_execz .LBB0_582
	s_load_dwordx16 s[12:27], s[62:63], 0x0
	s_lshl_b64 s[0:1], s[6:7], 13
	v_lshlrev_b32_e32 v12, 4, v0
	v_mov_b32_e32 v5, v13
	s_mov_b64 s[10:11], 0
	s_waitcnt lgkmcnt(0)
	s_add_u32 s0, s22, s0
	s_addc_u32 s1, s23, s1
	s_add_u32 s0, s0, 0x1540000
	s_addc_u32 s1, s1, 0
	v_lshl_add_u64 v[10:11], s[0:1], 0, v[12:13]
	s_lshl_b64 s[0:1], s[6:7], 12
	s_add_u32 s0, s34, s0
	s_addc_u32 s1, s35, s1
	v_lshl_add_u64 v[8:9], s[0:1], 0, v[4:5]
	s_mov_b64 s[0:1], 0x177a0000
	v_lshl_add_u64 v[12:13], v[8:9], 0, s[0:1]
	s_mov_b32 s0, 0xf0000
	s_mov_b32 s1, 0x1e0000
	s_mov_b32 s2, 0x2d0000
	s_mov_b32 s3, 0x78000
	s_mov_b32 s4, 0x168000
	s_mov_b32 s5, 0x258000
	s_mov_b64 s[12:13], 0x78000
	s_mov_b64 s[14:15], 0x780000
	s_mov_b64 s[18:19], 0x3c0000
	s_mov_b64 s[20:21], 0xe1000
	s_mov_b64 s[24:25], 0x6abfff
	v_mov_b64_e32 v[8:9], v[2:3]
	s_mov_b64 s[42:43], 0xf0000
	s_mov_b64 s[44:45], 0x78000
	s_mov_b64 s[46:47], 0xf00000
	s_mov_b64 s[48:49], 0x69000
	s_mov_b64 s[50:51], 0x6ac000
	s_mov_b64 s[40:41], exec
	v_lshl_add_u64 v[60:61], v[8:9], 0, s[20:21]
	v_cmp_ge_u64_e32 vcc, s[24:25], v[60:61]
	s_and_b64 exec, exec, vcc
	s_cbranch_execz .Lcv16_done

.LBB0_582:
	s_or_b64 exec, exec, s[8:9]
	s_mov_b64 s[0:1], 0x6ac000
	v_cmp_gt_u64_e32 vcc, s[0:1], v[8:9]
	s_and_saveexec_b64 s[8:9], vcc
	s_cbranch_execz .LBB0_585
	s_load_dwordx16 s[12:27], s[62:63], 0x0
	v_lshl_add_u64 v[12:13], v[8:9], 3, s[34:35]
	s_mov_b64 s[0:1], 0x177a0000
	v_lshl_add_u64 v[12:13], v[12:13], 0, s[0:1]
	s_mov_b32 s0, 0xffff1000
	s_mov_b32 s1, -1
	s_waitcnt lgkmcnt(0)
	s_add_u32 s22, s22, 0x1540000
	s_addc_u32 s23, s23, 0
	v_lshl_add_u64 v[10:11], v[8:9], 4, s[22:23]
	v_lshl_add_u64 v[8:9], v[8:9], 0, s[0:1]
	s_mov_b64 s[10:11], 0
	s_mov_b64 s[12:13], 0xf0000
	s_mov_b64 s[14:15], 0x78000
	s_mov_b64 s[18:19], 0xf000
	s_mov_b64 s[20:21], 0x69cfff
